# L10 fused-LN epilogue: pass-2 output stores issued after the second exchange's row-stat store (counted wait) so their drain overlaps the exchange
# baseline (speedup 1.0000x reference)
;   DI void fused(AccT& acc, const Unit& u, LAS unsigned char* lds, int tid, int wr, int wc, int fr, int fq) const {
;     ...
;     { f32x4 g[2][2], bb[2][2];
; #pragma unroll
;       for (int bj = 0; bj < 2; ++bj)
; #pragma unroll
;         for (int n = 0; n < 2; ++n) { g[bj][n] = *(const f32x4*)(gam + col0 + bj * HALF + n * 16); bb[bj][n] = *(const f32x4*)(bet + col0 + bj * HALF + n * 16); }
; #pragma unroll
;       for (int ai = 0; ai < 2; ++ai)
; #pragma unroll
;         for (int m = 0; m < 4; ++m) { const int rl = ai * 128 + wr * 64 + m * 16 + fr; const float mean = red[2048 + rl * 2], rstd = red[2048 + rl * 2 + 1];
;           float* xo = xout + (size_t)(u.pm * BM + rl) * DM + col0;
; #pragma unroll
;           for (int bj = 0; bj < 2; ++bj)
; #pragma unroll
;             for (int n = 0; n < 2; ++n) { f32x4 o;
; #pragma unroll
;               for (int j = 0; j < 4; ++j) { o[j] = (acc[ai][bj][m][n][j] - mean) * rstd * g[bj][n][j] + bb[bj][n][j]; acc[ai][bj][m][n][j] = o[j]; }
;               *(f32x4*)(xo + bj * HALF + n * 16) = o; } } }
.LBB0_1822:
	s_or_b64 exec, exec, s[14:15]
	s_lshl_b64 s[14:15], s[58:59], 13
	v_readlane_b32 s36, v252, 15
	v_readlane_b32 s37, v252, 16
	s_add_u32 s16, s36, s14
	v_readlane_b32 s38, v252, 17
	s_addc_u32 s17, s37, s15
	v_readlane_b32 s39, v252, 18
	s_add_u32 s14, s38, s14
	s_addc_u32 s15, s39, s15
	v_lshl_add_u64 v[130:131], s[16:17], 0, v[180:181]
	s_waitcnt lgkmcnt(0)
	s_barrier
	v_lshl_add_u64 v[132:133], s[14:15], 0, v[180:181]
	global_load_dwordx4 v[170:173], v[130:131], off
	global_load_dwordx4 v[174:177], v[132:133], off
	global_load_dwordx4 v[162:165], v[130:131], off offset:64
	global_load_dwordx4 v[166:169], v[132:133], off offset:64
	global_load_dwordx4 v[154:157], v[130:131], off offset:512
	global_load_dwordx4 v[158:161], v[132:133], off offset:512
	global_load_dwordx4 v[150:153], v[130:131], off offset:576
	global_load_dwordx4 v[146:149], v[132:133], off offset:576
	v_add_u32_e32 v184, s22, v198
	v_lshlrev_b32_e32 v130, 3, v198
	v_ashrrev_i32_e32 v185, 31, v184
	v_readlane_b32 s14, v251, 26
	v_add_u32_e32 v207, 0, v130
	v_lshlrev_b64 v[130:131], 13, v[184:185]
	v_readlane_b32 s15, v251, 27
	v_or_b32_e32 v132, 16, v198
	ds_read_b64 v[202:203], v207 offset:8192
	v_lshl_add_u64 v[130:131], s[14:15], 0, v[130:131]
	v_lshl_add_u64 v[200:201], v[130:131], 0, v[180:181]
	v_lshlrev_b32_e32 v130, 3, v132
	v_add_u32_e32 v208, 0, v130
	ds_read_b64 v[130:131], v208 offset:8192
	v_add_u32_e32 v186, s22, v132
	v_ashrrev_i32_e32 v187, 31, v186
	v_lshlrev_b64 v[132:133], 13, v[186:187]
	v_lshl_add_u64 v[132:133], s[14:15], 0, v[132:133]
	s_waitcnt lgkmcnt(0)
	v_pk_add_f32 v[98:99], v[98:99], v[130:131] op_sel_hi:[1,0] neg_lo:[0,1] neg_hi:[0,1]
	v_pk_add_f32 v[100:101], v[100:101], v[130:131] op_sel_hi:[1,0] neg_lo:[0,1] neg_hi:[0,1]
	v_pk_add_f32 v[94:95], v[94:95], v[130:131] op_sel_hi:[1,0] neg_lo:[0,1] neg_hi:[0,1]
	v_pk_add_f32 v[96:97], v[96:97], v[130:131] op_sel_hi:[1,0] neg_lo:[0,1] neg_hi:[0,1]
	v_pk_add_f32 v[90:91], v[90:91], v[130:131] op_sel_hi:[1,0] neg_lo:[0,1] neg_hi:[0,1]
	v_pk_add_f32 v[92:93], v[92:93], v[130:131] op_sel_hi:[1,0] neg_lo:[0,1] neg_hi:[0,1]
	v_pk_add_f32 v[86:87], v[86:87], v[130:131] op_sel_hi:[1,0] neg_lo:[0,1] neg_hi:[0,1]
	v_pk_add_f32 v[88:89], v[88:89], v[130:131] op_sel_hi:[1,0] neg_lo:[0,1] neg_hi:[0,1]
	v_pk_mul_f32 v[98:99], v[130:131], v[98:99] op_sel:[1,0]
	v_pk_mul_f32 v[100:101], v[130:131], v[100:101] op_sel:[1,0]
	v_pk_mul_f32 v[94:95], v[130:131], v[94:95] op_sel:[1,0]
	v_pk_mul_f32 v[96:97], v[130:131], v[96:97] op_sel:[1,0]
	v_pk_mul_f32 v[90:91], v[130:131], v[90:91] op_sel:[1,0]
	v_pk_mul_f32 v[92:93], v[130:131], v[92:93] op_sel:[1,0]
	v_pk_mul_f32 v[86:87], v[130:131], v[86:87] op_sel:[1,0]
	v_pk_mul_f32 v[88:89], v[130:131], v[88:89] op_sel:[1,0]
	v_lshl_add_u64 v[132:133], v[132:133], 0, v[180:181]
	v_pk_add_f32 v[110:111], v[110:111], v[202:203] op_sel_hi:[1,0] neg_lo:[0,1] neg_hi:[0,1]
	v_pk_add_f32 v[112:113], v[112:113], v[202:203] op_sel_hi:[1,0] neg_lo:[0,1] neg_hi:[0,1]
	v_pk_mul_f32 v[110:111], v[202:203], v[110:111] op_sel:[1,0]
	v_pk_mul_f32 v[112:113], v[202:203], v[112:113] op_sel:[1,0]
	v_pk_add_f32 v[106:107], v[106:107], v[202:203] op_sel_hi:[1,0] neg_lo:[0,1] neg_hi:[0,1]
	v_pk_add_f32 v[108:109], v[108:109], v[202:203] op_sel_hi:[1,0] neg_lo:[0,1] neg_hi:[0,1]
	v_pk_mul_f32 v[106:107], v[202:203], v[106:107] op_sel:[1,0]
	v_pk_mul_f32 v[108:109], v[202:203], v[108:109] op_sel:[1,0]
	v_pk_add_f32 v[102:103], v[102:103], v[202:203] op_sel_hi:[1,0] neg_lo:[0,1] neg_hi:[0,1]
	v_pk_add_f32 v[104:105], v[104:105], v[202:203] op_sel_hi:[1,0] neg_lo:[0,1] neg_hi:[0,1]
	v_pk_mul_f32 v[102:103], v[202:203], v[102:103] op_sel:[1,0]
	v_pk_mul_f32 v[104:105], v[202:203], v[104:105] op_sel:[1,0]
	v_pk_add_f32 v[2:3], v[2:3], v[202:203] op_sel_hi:[1,0] neg_lo:[0,1] neg_hi:[0,1]
	v_pk_add_f32 v[4:5], v[4:5], v[202:203] op_sel_hi:[1,0] neg_lo:[0,1] neg_hi:[0,1]
	v_pk_mul_f32 v[2:3], v[202:203], v[2:3] op_sel:[1,0]
	v_pk_mul_f32 v[4:5], v[202:203], v[4:5] op_sel:[1,0]
	v_readlane_b32 s40, v252, 19
	v_readlane_b32 s41, v252, 20
	v_readlane_b32 s42, v252, 21
	v_readlane_b32 s43, v252, 22
	s_waitcnt vmcnt(6)
	v_pk_fma_f32 v[98:99], v[170:171], v[98:99], v[174:175]
	v_pk_fma_f32 v[100:101], v[172:173], v[100:101], v[176:177]
	s_waitcnt vmcnt(4)
	v_pk_fma_f32 v[94:95], v[162:163], v[94:95], v[166:167]
	v_pk_fma_f32 v[96:97], v[164:165], v[96:97], v[168:169]
	s_waitcnt vmcnt(2)
	v_pk_fma_f32 v[90:91], v[154:155], v[90:91], v[158:159]
	v_pk_fma_f32 v[92:93], v[156:157], v[92:93], v[160:161]
	s_waitcnt vmcnt(0)
	v_pk_fma_f32 v[86:87], v[150:151], v[86:87], v[146:147]
	v_pk_fma_f32 v[88:89], v[152:153], v[88:89], v[148:149]
	v_mov_b32_e32 v232, v132
	v_mov_b32_e32 v233, v133
	v_or_b32_e32 v132, 32, v198
	v_lshlrev_b32_e32 v130, 3, v132
	v_add_u32_e32 v214, 0, v130
	ds_read_b64 v[130:131], v214 offset:8192
	v_add_u32_e32 v188, s22, v132
	v_ashrrev_i32_e32 v189, 31, v188
	v_lshlrev_b64 v[132:133], 13, v[188:189]
	v_lshl_add_u64 v[132:133], s[14:15], 0, v[132:133]
	s_waitcnt lgkmcnt(0)
;   DI void fused(AccT& acc, const Unit& u, LAS unsigned char* lds, int tid, int wr, int wc, int fr, int fq) const {
;     ...
;       for (int ai = 0; ai < 2; ++ai)
; #pragma unroll
;         for (int m = 0; m < 4; ++m) { const int rl = ai * 128 + wr * 64 + m * 16 + fr; const float mean = red[2048 + rl * 2], rstd = red[2048 + rl * 2 + 1];
;           float* xo = xout + (size_t)(u.pm * BM + rl) * DM + col0;
; #pragma unroll
;           for (int bj = 0; bj < 2; ++bj)
; #pragma unroll
;             for (int n = 0; n < 2; ++n) { f32x4 o;
; #pragma unroll
;               for (int j = 0; j < 4; ++j) { o[j] = (acc[ai][bj][m][n][j] - mean) * rstd * g[bj][n][j] + bb[bj][n][j]; acc[ai][bj][m][n][j] = o[j]; }
;               *(f32x4*)(xo + bj * HALF + n * 16) = o; } } }
	v_pk_add_f32 v[126:127], v[126:127], v[130:131] op_sel_hi:[1,0] neg_lo:[0,1] neg_hi:[0,1]
	v_pk_add_f32 v[128:129], v[128:129], v[130:131] op_sel_hi:[1,0] neg_lo:[0,1] neg_hi:[0,1]
	v_pk_add_f32 v[122:123], v[122:123], v[130:131] op_sel_hi:[1,0] neg_lo:[0,1] neg_hi:[0,1]
	v_pk_add_f32 v[124:125], v[124:125], v[130:131] op_sel_hi:[1,0] neg_lo:[0,1] neg_hi:[0,1]
	v_pk_add_f32 v[118:119], v[118:119], v[130:131] op_sel_hi:[1,0] neg_lo:[0,1] neg_hi:[0,1]
	v_pk_add_f32 v[120:121], v[120:121], v[130:131] op_sel_hi:[1,0] neg_lo:[0,1] neg_hi:[0,1]
	v_pk_add_f32 v[114:115], v[114:115], v[130:131] op_sel_hi:[1,0] neg_lo:[0,1] neg_hi:[0,1]
	v_pk_add_f32 v[116:117], v[116:117], v[130:131] op_sel_hi:[1,0] neg_lo:[0,1] neg_hi:[0,1]
	v_pk_mul_f32 v[126:127], v[130:131], v[126:127] op_sel:[1,0]
	v_pk_mul_f32 v[128:129], v[130:131], v[128:129] op_sel:[1,0]
	v_pk_mul_f32 v[122:123], v[130:131], v[122:123] op_sel:[1,0]
	v_pk_mul_f32 v[124:125], v[130:131], v[124:125] op_sel:[1,0]
	v_pk_mul_f32 v[118:119], v[130:131], v[118:119] op_sel:[1,0]
	v_pk_mul_f32 v[120:121], v[130:131], v[120:121] op_sel:[1,0]
	v_pk_mul_f32 v[114:115], v[130:131], v[114:115] op_sel:[1,0]
	v_pk_mul_f32 v[116:117], v[130:131], v[116:117] op_sel:[1,0]
	v_or_b32_e32 v130, 48, v198
	v_lshlrev_b32_e32 v131, 3, v130
	v_lshl_add_u64 v[132:133], v[132:133], 0, v[180:181]
	v_pk_fma_f32 v[126:127], v[170:171], v[126:127], v[174:175]
	v_pk_fma_f32 v[128:129], v[172:173], v[128:129], v[176:177]
	v_pk_fma_f32 v[122:123], v[162:163], v[122:123], v[166:167]
	v_pk_fma_f32 v[124:125], v[164:165], v[124:125], v[168:169]
	v_pk_fma_f32 v[118:119], v[154:155], v[118:119], v[158:159]
	v_pk_fma_f32 v[120:121], v[156:157], v[120:121], v[160:161]
	v_pk_fma_f32 v[114:115], v[150:151], v[114:115], v[146:147]
	v_pk_fma_f32 v[116:117], v[152:153], v[116:117], v[148:149]
	v_add_u32_e32 v215, 0, v131
	v_mov_b32_e32 v234, v132
	v_mov_b32_e32 v235, v133
	ds_read_b64 v[132:133], v215 offset:8192
	v_add_u32_e32 v192, s22, v130
	v_ashrrev_i32_e32 v193, 31, v192
	v_lshlrev_b64 v[130:131], 13, v[192:193]
	v_lshl_add_u64 v[130:131], s[14:15], 0, v[130:131]
	s_waitcnt lgkmcnt(0)
	v_pk_add_f32 v[22:23], v[22:23], v[132:133] op_sel_hi:[1,0] neg_lo:[0,1] neg_hi:[0,1]
	v_pk_add_f32 v[46:47], v[46:47], v[132:133] op_sel_hi:[1,0] neg_lo:[0,1] neg_hi:[0,1]
	v_pk_add_f32 v[34:35], v[34:35], v[132:133] op_sel_hi:[1,0] neg_lo:[0,1] neg_hi:[0,1]
	v_pk_add_f32 v[26:27], v[26:27], v[132:133] op_sel_hi:[1,0] neg_lo:[0,1] neg_hi:[0,1]
	v_pk_mul_f32 v[22:23], v[132:133], v[22:23] op_sel:[1,0]
	v_lshl_add_u64 v[190:191], v[130:131], 0, v[180:181]
	v_pk_mul_f32 v[46:47], v[132:133], v[46:47] op_sel:[1,0]
	v_pk_mul_f32 v[34:35], v[132:133], v[34:35] op_sel:[1,0]
	v_pk_mul_f32 v[26:27], v[132:133], v[26:27] op_sel:[1,0]
	v_pk_fma_f32 v[130:131], v[150:151], v[22:23], v[146:147]
	v_pk_add_f32 v[22:23], v[24:25], v[132:133] op_sel_hi:[1,0] neg_lo:[0,1] neg_hi:[0,1]
	v_pk_fma_f32 v[142:143], v[170:171], v[46:47], v[174:175]
	v_pk_add_f32 v[46:47], v[48:49], v[132:133] op_sel_hi:[1,0] neg_lo:[0,1] neg_hi:[0,1]
	v_pk_fma_f32 v[138:139], v[162:163], v[34:35], v[166:167]
	v_pk_add_f32 v[34:35], v[36:37], v[132:133] op_sel_hi:[1,0] neg_lo:[0,1] neg_hi:[0,1]
	v_pk_fma_f32 v[134:135], v[154:155], v[26:27], v[158:159]
	v_pk_add_f32 v[26:27], v[28:29], v[132:133] op_sel_hi:[1,0] neg_lo:[0,1] neg_hi:[0,1]
	v_pk_mul_f32 v[22:23], v[132:133], v[22:23] op_sel:[1,0]
	v_pk_mul_f32 v[46:47], v[132:133], v[46:47] op_sel:[1,0]
	v_pk_mul_f32 v[34:35], v[132:133], v[34:35] op_sel:[1,0]
	v_pk_mul_f32 v[26:27], v[132:133], v[26:27] op_sel:[1,0]
	v_pk_fma_f32 v[132:133], v[152:153], v[22:23], v[148:149]
	v_add_u32_e32 v22, 0x80, v198
	v_lshlrev_b32_e32 v23, 3, v22
	v_add_u32_e32 v216, 0, v23
	v_pk_fma_f32 v[144:145], v[172:173], v[46:47], v[176:177]
	v_pk_fma_f32 v[140:141], v[164:165], v[34:35], v[168:169]
	v_pk_fma_f32 v[136:137], v[156:157], v[26:27], v[160:161]
	ds_read_b64 v[24:25], v216 offset:8192
	v_mov_b32_e32 v236, v190
	v_mov_b32_e32 v237, v191
	v_add_u32_e32 v190, s22, v22
	v_ashrrev_i32_e32 v191, 31, v190
	v_lshlrev_b64 v[22:23], 13, v[190:191]
	v_lshl_add_u64 v[22:23], s[14:15], 0, v[22:23]
	v_lshl_add_u64 v[194:195], v[22:23], 0, v[180:181]
	s_waitcnt lgkmcnt(0)
	v_pk_add_f32 v[22:23], v[82:83], v[24:25] op_sel_hi:[1,0] neg_lo:[0,1] neg_hi:[0,1]
	v_pk_fma_f32 v[110:111], v[170:171], v[110:111], v[174:175]
	v_pk_mul_f32 v[22:23], v[24:25], v[22:23] op_sel:[1,0]
	v_pk_fma_f32 v[112:113], v[172:173], v[112:113], v[176:177]
	v_pk_fma_f32 v[46:47], v[170:171], v[22:23], v[174:175]
	v_pk_add_f32 v[22:23], v[84:85], v[24:25] op_sel_hi:[1,0] neg_lo:[0,1] neg_hi:[0,1]
	v_pk_fma_f32 v[106:107], v[162:163], v[106:107], v[166:167]
	v_pk_mul_f32 v[22:23], v[24:25], v[22:23] op_sel:[1,0]
	v_pk_fma_f32 v[108:109], v[164:165], v[108:109], v[168:169]
	v_pk_fma_f32 v[48:49], v[172:173], v[22:23], v[176:177]
	v_pk_add_f32 v[22:23], v[78:79], v[24:25] op_sel_hi:[1,0] neg_lo:[0,1] neg_hi:[0,1]
	v_mov_b32_e32 v238, v194
	v_mov_b32_e32 v239, v195
	v_pk_mul_f32 v[22:23], v[24:25], v[22:23] op_sel:[1,0]
	v_pk_fma_f32 v[102:103], v[154:155], v[102:103], v[158:159]
	v_pk_fma_f32 v[34:35], v[162:163], v[22:23], v[166:167]
	v_pk_add_f32 v[22:23], v[80:81], v[24:25] op_sel_hi:[1,0] neg_lo:[0,1] neg_hi:[0,1]
	v_pk_fma_f32 v[104:105], v[156:157], v[104:105], v[160:161]
	v_pk_mul_f32 v[22:23], v[24:25], v[22:23] op_sel:[1,0]
	v_pk_fma_f32 v[2:3], v[150:151], v[2:3], v[146:147]
	v_pk_fma_f32 v[36:37], v[164:165], v[22:23], v[168:169]
	v_pk_add_f32 v[22:23], v[74:75], v[24:25] op_sel_hi:[1,0] neg_lo:[0,1] neg_hi:[0,1]
	v_pk_mul_f32 v[22:23], v[24:25], v[22:23] op_sel:[1,0]
	v_mov_b32_e32 v83, v149
	v_pk_fma_f32 v[26:27], v[154:155], v[22:23], v[158:159]
	v_pk_add_f32 v[22:23], v[76:77], v[24:25] op_sel_hi:[1,0] neg_lo:[0,1] neg_hi:[0,1]
	v_mov_b32_e32 v240, v200
	v_mov_b32_e32 v241, v201
	v_pk_mul_f32 v[22:23], v[24:25], v[22:23] op_sel:[1,0]
	v_pk_fma_f32 v[28:29], v[156:157], v[22:23], v[160:161]
	v_pk_add_f32 v[22:23], v[70:71], v[24:25] op_sel_hi:[1,0] neg_lo:[0,1] neg_hi:[0,1]
	v_pk_add_f32 v[70:71], v[72:73], v[24:25] op_sel_hi:[1,0] neg_lo:[0,1] neg_hi:[0,1]
	v_add_u32_e32 v72, 0x90, v198
	v_pk_mul_f32 v[22:23], v[24:25], v[22:23] op_sel:[1,0]
	v_pk_mul_f32 v[24:25], v[24:25], v[70:71] op_sel:[1,0]
	v_lshlrev_b32_e32 v70, 3, v72
	v_add_u32_e32 v217, 0, v70
	ds_read_b64 v[70:71], v217 offset:8192
	v_pk_fma_f32 v[22:23], v[150:151], v[22:23], v[146:147]
	v_pk_fma_f32 v[24:25], v[152:153], v[24:25], v[148:149]
	v_add_u32_e32 v194, s22, v72
	v_ashrrev_i32_e32 v195, 31, v194
	v_lshlrev_b64 v[72:73], 13, v[194:195]
	s_waitcnt lgkmcnt(0)
;   DI void fused(AccT& acc, const Unit& u, LAS unsigned char* lds, int tid, int wr, int wc, int fr, int fq) const {
;     ...
;       for (int ai = 0; ai < 2; ++ai)
; #pragma unroll
;         for (int m = 0; m < 4; ++m) { const int rl = ai * 128 + wr * 64 + m * 16 + fr; const float mean = red[2048 + rl * 2], rstd = red[2048 + rl * 2 + 1];
;           float* xo = xout + (size_t)(u.pm * BM + rl) * DM + col0;
; #pragma unroll
;           for (int bj = 0; bj < 2; ++bj)
; #pragma unroll
;             for (int n = 0; n < 2; ++n) { f32x4 o;
; #pragma unroll
;               for (int j = 0; j < 4; ++j) { o[j] = (acc[ai][bj][m][n][j] - mean) * rstd * g[bj][n][j] + bb[bj][n][j]; acc[ai][bj][m][n][j] = o[j]; }
;               *(f32x4*)(xo + bj * HALF + n * 16) = o; } } }
	v_pk_add_f32 v[66:67], v[66:67], v[70:71] op_sel_hi:[1,0] neg_lo:[0,1] neg_hi:[0,1]
	v_pk_add_f32 v[68:69], v[68:69], v[70:71] op_sel_hi:[1,0] neg_lo:[0,1] neg_hi:[0,1]
	v_pk_add_f32 v[62:63], v[62:63], v[70:71] op_sel_hi:[1,0] neg_lo:[0,1] neg_hi:[0,1]
	v_pk_add_f32 v[64:65], v[64:65], v[70:71] op_sel_hi:[1,0] neg_lo:[0,1] neg_hi:[0,1]
	v_pk_add_f32 v[58:59], v[58:59], v[70:71] op_sel_hi:[1,0] neg_lo:[0,1] neg_hi:[0,1]
	v_pk_add_f32 v[60:61], v[60:61], v[70:71] op_sel_hi:[1,0] neg_lo:[0,1] neg_hi:[0,1]
	v_pk_add_f32 v[54:55], v[54:55], v[70:71] op_sel_hi:[1,0] neg_lo:[0,1] neg_hi:[0,1]
	v_pk_add_f32 v[56:57], v[56:57], v[70:71] op_sel_hi:[1,0] neg_lo:[0,1] neg_hi:[0,1]
	v_lshl_add_u64 v[72:73], s[14:15], 0, v[72:73]
	v_pk_mul_f32 v[66:67], v[70:71], v[66:67] op_sel:[1,0]
	v_pk_mul_f32 v[68:69], v[70:71], v[68:69] op_sel:[1,0]
	v_pk_mul_f32 v[62:63], v[70:71], v[62:63] op_sel:[1,0]
	v_pk_mul_f32 v[64:65], v[70:71], v[64:65] op_sel:[1,0]
	v_pk_mul_f32 v[58:59], v[70:71], v[58:59] op_sel:[1,0]
	v_pk_mul_f32 v[60:61], v[70:71], v[60:61] op_sel:[1,0]
	v_pk_mul_f32 v[54:55], v[70:71], v[54:55] op_sel:[1,0]
	v_pk_mul_f32 v[56:57], v[70:71], v[56:57] op_sel:[1,0]
	v_lshl_add_u64 v[72:73], v[72:73], 0, v[180:181]
	v_pk_fma_f32 v[66:67], v[170:171], v[66:67], v[174:175]
	v_pk_fma_f32 v[68:69], v[172:173], v[68:69], v[176:177]
	v_pk_fma_f32 v[62:63], v[162:163], v[62:63], v[166:167]
	v_pk_fma_f32 v[64:65], v[164:165], v[64:65], v[168:169]
	v_pk_fma_f32 v[58:59], v[154:155], v[58:59], v[158:159]
	v_pk_fma_f32 v[60:61], v[156:157], v[60:61], v[160:161]
	v_pk_fma_f32 v[54:55], v[150:151], v[54:55], v[146:147]
	v_pk_fma_f32 v[56:57], v[152:153], v[56:57], v[148:149]
	v_mov_b32_e32 v242, v72
	v_mov_b32_e32 v243, v73
	v_add_u32_e32 v72, 0xa0, v198
	v_lshlrev_b32_e32 v70, 3, v72
	v_add_u32_e32 v218, 0, v70
	ds_read_b64 v[70:71], v218 offset:8192
	v_add_u32_e32 v196, s22, v72
	v_ashrrev_i32_e32 v197, 31, v196
	v_lshlrev_b64 v[72:73], 13, v[196:197]
	v_lshl_add_u64 v[72:73], s[14:15], 0, v[72:73]
	s_waitcnt lgkmcnt(0)
	v_pk_add_f32 v[50:51], v[50:51], v[70:71] op_sel_hi:[1,0] neg_lo:[0,1] neg_hi:[0,1]
	v_pk_add_f32 v[52:53], v[52:53], v[70:71] op_sel_hi:[1,0] neg_lo:[0,1] neg_hi:[0,1]
	v_pk_add_f32 v[42:43], v[42:43], v[70:71] op_sel_hi:[1,0] neg_lo:[0,1] neg_hi:[0,1]
	v_pk_add_f32 v[44:45], v[44:45], v[70:71] op_sel_hi:[1,0] neg_lo:[0,1] neg_hi:[0,1]
	v_pk_add_f32 v[38:39], v[38:39], v[70:71] op_sel_hi:[1,0] neg_lo:[0,1] neg_hi:[0,1]
	v_pk_add_f32 v[40:41], v[40:41], v[70:71] op_sel_hi:[1,0] neg_lo:[0,1] neg_hi:[0,1]
	v_pk_add_f32 v[30:31], v[30:31], v[70:71] op_sel_hi:[1,0] neg_lo:[0,1] neg_hi:[0,1]
	v_pk_add_f32 v[32:33], v[32:33], v[70:71] op_sel_hi:[1,0] neg_lo:[0,1] neg_hi:[0,1]
	v_pk_mul_f32 v[50:51], v[70:71], v[50:51] op_sel:[1,0]
	v_pk_mul_f32 v[52:53], v[70:71], v[52:53] op_sel:[1,0]
	v_pk_mul_f32 v[42:43], v[70:71], v[42:43] op_sel:[1,0]
	v_pk_mul_f32 v[44:45], v[70:71], v[44:45] op_sel:[1,0]
	v_pk_mul_f32 v[38:39], v[70:71], v[38:39] op_sel:[1,0]
	v_pk_mul_f32 v[40:41], v[70:71], v[40:41] op_sel:[1,0]
	v_pk_mul_f32 v[30:31], v[70:71], v[30:31] op_sel:[1,0]
	v_pk_mul_f32 v[32:33], v[70:71], v[32:33] op_sel:[1,0]
	v_lshl_add_u64 v[72:73], v[72:73], 0, v[180:181]
	v_pk_fma_f32 v[50:51], v[170:171], v[50:51], v[174:175]
	v_pk_fma_f32 v[52:53], v[172:173], v[52:53], v[176:177]
	v_pk_fma_f32 v[42:43], v[162:163], v[42:43], v[166:167]
	v_pk_fma_f32 v[44:45], v[164:165], v[44:45], v[168:169]
	v_pk_fma_f32 v[38:39], v[154:155], v[38:39], v[158:159]
	v_pk_fma_f32 v[40:41], v[156:157], v[40:41], v[160:161]
	v_pk_fma_f32 v[30:31], v[150:151], v[30:31], v[146:147]
	v_pk_fma_f32 v[32:33], v[152:153], v[32:33], v[148:149]
	v_mov_b32_e32 v244, v72
	v_mov_b32_e32 v245, v73
	v_add_u32_e32 v72, 0xb0, v198
	v_lshlrev_b32_e32 v70, 3, v72
	v_add_u32_e32 v219, 0, v70
	ds_read_b64 v[70:71], v219 offset:8192
	v_add_u32_e32 v198, s22, v72
	v_ashrrev_i32_e32 v199, 31, v198
	v_lshlrev_b64 v[72:73], 13, v[198:199]
	v_lshl_add_u64 v[72:73], s[14:15], 0, v[72:73]
	s_waitcnt lgkmcnt(0)
; DI void ln_exchange(const AccT& acc, LAS float* red, float* stats, unsigned* cnt, int pm, int pn, int tid, int wr, int wc, int fr, int fq) {
;     ...
;       float s1 = 0.f, s2 = 0.f;
; #pragma unroll
;       for (int bj = 0; bj < 2; ++bj)
; #pragma unroll
;         for (int n = 0; n < 2; ++n)
; #pragma unroll
;           for (int j = 0; j < 4; ++j) { const float x = acc[ai][bj][m][n][j]; s1 += x; s2 += x * x; }
;       s1 += __shfl_xor(s1, 16); s2 += __shfl_xor(s2, 16); s1 += __shfl_xor(s1, 32); s2 += __shfl_xor(s2, 32);
;       if (fq == 0) { const int rl = ai * 128 + wr * 64 + m * 16 + fr; red[(rl * 4 + wc) * 2] = s1; red[(rl * 4 + wc) * 2 + 1] = s2; }
;   DI void fused(AccT& acc, const Unit& u, LAS unsigned char* lds, int tid, int wr, int wc, int fr, int fq) const {
;     ...
;       for (int ai = 0; ai < 2; ++ai)
; #pragma unroll
;         for (int m = 0; m < 4; ++m) { const int rl = ai * 128 + wr * 64 + m * 16 + fr; const float mean = red[2048 + rl * 2], rstd = red[2048 + rl * 2 + 1];
;           float* xo = xout + (size_t)(u.pm * BM + rl) * DM + col0;
; #pragma unroll
;           for (int bj = 0; bj < 2; ++bj)
; #pragma unroll
;             for (int n = 0; n < 2; ++n) { f32x4 o;
; #pragma unroll
;               for (int j = 0; j < 4; ++j) { o[j] = (acc[ai][bj][m][n][j] - mean) * rstd * g[bj][n][j] + bb[bj][n][j]; acc[ai][bj][m][n][j] = o[j]; }
;               *(f32x4*)(xo + bj * HALF + n * 16) = o; } } }
	v_pk_add_f32 v[18:19], v[18:19], v[70:71] op_sel_hi:[1,0] neg_lo:[0,1] neg_hi:[0,1]
	v_pk_add_f32 v[20:21], v[20:21], v[70:71] op_sel_hi:[1,0] neg_lo:[0,1] neg_hi:[0,1]
	v_pk_add_f32 v[14:15], v[14:15], v[70:71] op_sel_hi:[1,0] neg_lo:[0,1] neg_hi:[0,1]
	v_pk_add_f32 v[16:17], v[16:17], v[70:71] op_sel_hi:[1,0] neg_lo:[0,1] neg_hi:[0,1]
	v_pk_add_f32 v[10:11], v[10:11], v[70:71] op_sel_hi:[1,0] neg_lo:[0,1] neg_hi:[0,1]
	v_pk_add_f32 v[12:13], v[12:13], v[70:71] op_sel_hi:[1,0] neg_lo:[0,1] neg_hi:[0,1]
	v_pk_add_f32 v[6:7], v[6:7], v[70:71] op_sel_hi:[1,0] neg_lo:[0,1] neg_hi:[0,1]
	v_pk_add_f32 v[8:9], v[8:9], v[70:71] op_sel_hi:[1,0] neg_lo:[0,1] neg_hi:[0,1]
	v_pk_mul_f32 v[18:19], v[70:71], v[18:19] op_sel:[1,0]
	v_pk_mul_f32 v[20:21], v[70:71], v[20:21] op_sel:[1,0]
	v_pk_mul_f32 v[14:15], v[70:71], v[14:15] op_sel:[1,0]
	v_pk_mul_f32 v[16:17], v[70:71], v[16:17] op_sel:[1,0]
	v_pk_mul_f32 v[10:11], v[70:71], v[10:11] op_sel:[1,0]
	v_pk_mul_f32 v[12:13], v[70:71], v[12:13] op_sel:[1,0]
	v_pk_mul_f32 v[6:7], v[70:71], v[6:7] op_sel:[1,0]
	v_pk_mul_f32 v[8:9], v[70:71], v[8:9] op_sel:[1,0]
	v_lshl_add_u64 v[72:73], v[72:73], 0, v[180:181]
	v_pk_fma_f32 v[18:19], v[170:171], v[18:19], v[174:175]
	v_pk_fma_f32 v[20:21], v[172:173], v[20:21], v[176:177]
	v_pk_fma_f32 v[14:15], v[162:163], v[14:15], v[166:167]
	v_pk_fma_f32 v[16:17], v[164:165], v[16:17], v[168:169]
	v_pk_fma_f32 v[10:11], v[154:155], v[10:11], v[158:159]
	v_pk_fma_f32 v[12:13], v[156:157], v[12:13], v[160:161]
	v_pk_fma_f32 v[6:7], v[150:151], v[6:7], v[146:147]
	v_pk_fma_f32 v[8:9], v[152:153], v[8:9], v[148:149]
	v_mov_b32_e32 v246, v72
	v_mov_b32_e32 v247, v73
	v_add_f32_e32 v72, 0, v110
	v_add_f32_e32 v72, v111, v72
	v_pk_mul_f32 v[70:71], v[110:111], v[110:111]
	v_add_f32_e32 v72, v112, v72
	v_add_f32_e32 v74, v113, v72
	v_pk_mul_f32 v[72:73], v[112:113], v[112:113]
	v_add_f32_e32 v70, v70, v71
	v_add_f32_e32 v74, v106, v74
	v_add_f32_e32 v70, v72, v70
	v_add_f32_e32 v76, v107, v74
	v_pk_mul_f32 v[74:75], v[106:107], v[106:107]
	v_add_f32_e32 v70, v73, v70
	v_add_f32_e32 v76, v108, v76
	v_add_f32_e32 v70, v74, v70
	v_add_f32_e32 v78, v109, v76
	v_pk_mul_f32 v[76:77], v[108:109], v[108:109]
	v_add_f32_e32 v70, v75, v70
	v_add_f32_e32 v78, v102, v78
	v_add_f32_e32 v70, v76, v70
	v_add_f32_e32 v80, v103, v78
	v_pk_mul_f32 v[78:79], v[102:103], v[102:103]
	v_add_f32_e32 v70, v77, v70
	v_add_f32_e32 v80, v104, v80
	v_add_f32_e32 v70, v78, v70
	v_add_f32_e32 v82, v105, v80
	v_pk_mul_f32 v[80:81], v[104:105], v[104:105]
	v_add_f32_e32 v70, v79, v70
	v_add_f32_e32 v70, v80, v70
	v_add_f32_e32 v70, v81, v70
	v_fmac_f32_e32 v70, v2, v2
	v_pk_fma_f32 v[146:147], v[152:153], v[4:5], v[148:149]
	v_pk_fma_f32 v[70:71], v[2:3], v[2:3], v[70:71] op_sel_hi:[1,1,0]
	v_pk_mul_f32 v[72:73], v[152:153], v[4:5]
	v_pk_mul_f32 v[4:5], v[146:147], v[146:147]
	v_mov_b32_e32 v76, v149
	v_mov_b32_e32 v77, v4
	v_mov_b32_e32 v70, v73
	v_add_f32_e32 v82, v2, v82
	v_mov_b32_e32 v72, v3
	v_pk_add_f32 v[148:149], v[76:77], v[70:71]
	v_pk_add_f32 v[74:75], v[82:83], v[72:73]
	v_mov_b32_e32 v4, v146
	v_mov_b32_e32 v5, v148
	global_store_dwordx4 v[200:201], v[2:5], off offset:576
	s_nop 1
	v_pk_mul_f32 v[70:71], v[146:147], v[74:75]
	v_pk_add_f32 v[4:5], v[146:147], v[74:75]
	s_nop 0
	v_mov_b32_e32 v5, v71
	v_pk_add_f32 v[4:5], v[148:149], v[4:5]
	ds_bpermute_b32 v70, v0, v4
	ds_bpermute_b32 v71, v0, v5
	s_barrier
	s_waitcnt lgkmcnt(0)
	v_pk_add_f32 v[4:5], v[4:5], v[70:71]
	ds_bpermute_b32 v70, v205, v4
	ds_bpermute_b32 v71, v205, v5
	s_and_saveexec_b64 s[14:15], s[0:1]
	s_cbranch_execz .LBB0_1824
	s_lshl_b32 s9, s28, 11
	s_add_i32 s9, s23, s9
	v_lshl_add_u32 v72, v204, 5, s9
	s_waitcnt lgkmcnt(0)
	v_pk_add_f32 v[4:5], v[4:5], v[70:71]
	ds_write_b64 v72, v[4:5]

; DI void ln_exchange(const AccT& acc, LAS float* red, float* stats, unsigned* cnt, int pm, int pn, int tid, int wr, int wc, int fr, int fq) {
;     ...
;     __hip_atomic_store(sp, a, __ATOMIC_RELAXED, __HIP_MEMORY_SCOPE_AGENT); __hip_atomic_store(sp + 1, b, __ATOMIC_RELAXED, __HIP_MEMORY_SCOPE_AGENT); }
;   asm volatile("s_waitcnt vmcnt(0)" ::: "memory");
;   __syncthreads();
;   if (tid == 0) {
;     __builtin_amdgcn_fence(__ATOMIC_RELEASE, "agent");
;     asm volatile("s_waitcnt vmcnt(0)" ::: "memory");
;     __hip_atomic_fetch_add(cnt + pm, 1u, __ATOMIC_RELAXED, __HIP_MEMORY_SCOPE_AGENT);
.LBB0_1840:
	s_or_b64 exec, exec, s[0:1]
	global_store_dwordx4 v[232:233], v[98:101], off
	global_store_dwordx4 v[232:233], v[94:97], off offset:64
	global_store_dwordx4 v[232:233], v[90:93], off offset:512
	global_store_dwordx4 v[232:233], v[86:89], off offset:576
	global_store_dwordx4 v[234:235], v[126:129], off
	global_store_dwordx4 v[234:235], v[122:125], off offset:64
	global_store_dwordx4 v[234:235], v[118:121], off offset:512
	global_store_dwordx4 v[234:235], v[114:117], off offset:576
	global_store_dwordx4 v[236:237], v[142:145], off
	global_store_dwordx4 v[236:237], v[138:141], off offset:64
	global_store_dwordx4 v[236:237], v[134:137], off offset:512
	global_store_dwordx4 v[236:237], v[130:133], off offset:576
	global_store_dwordx4 v[238:239], v[46:49], off
	global_store_dwordx4 v[238:239], v[34:37], off offset:64
	global_store_dwordx4 v[238:239], v[26:29], off offset:512
	global_store_dwordx4 v[238:239], v[22:25], off offset:576
	global_store_dwordx4 v[240:241], v[110:113], off
	global_store_dwordx4 v[240:241], v[106:109], off offset:64
	global_store_dwordx4 v[240:241], v[102:105], off offset:512
	global_store_dwordx4 v[242:243], v[66:69], off
	global_store_dwordx4 v[242:243], v[62:65], off offset:64
	global_store_dwordx4 v[242:243], v[58:61], off offset:512
	global_store_dwordx4 v[242:243], v[54:57], off offset:576
	global_store_dwordx4 v[244:245], v[50:53], off
	global_store_dwordx4 v[244:245], v[42:45], off offset:64
	global_store_dwordx4 v[244:245], v[38:41], off offset:512
	global_store_dwordx4 v[244:245], v[30:33], off offset:576
	global_store_dwordx4 v[246:247], v[18:21], off
	global_store_dwordx4 v[246:247], v[14:17], off offset:64
	global_store_dwordx4 v[246:247], v[10:13], off offset:512
	global_store_dwordx4 v[246:247], v[6:9], off offset:576
	s_waitcnt vmcnt(31)
	s_barrier
	s_and_saveexec_b64 s[0:1], s[4:5]
	s_cbranch_execz .LBB0_1857
	s_ashr_i32 s9, s8, 31
	s_lshl_b64 s[4:5], s[8:9], 2
	s_mov_b64 s[8:9], exec
	s_waitcnt vmcnt(31)
	s_waitcnt vmcnt(31)
	v_mbcnt_lo_u32_b32 v0, s8, 0
	s_add_u32 s4, s24, s4
	v_mbcnt_hi_u32_b32 v0, s9, v0
	s_addc_u32 s5, s25, s5
	v_cmp_eq_u32_e32 vcc, 0, v0
	s_and_saveexec_b64 s[10:11], vcc
	s_cbranch_execz .LBB0_1843
	s_bcnt1_i32_b64 s8, s[8:9]
	v_mov_b32_e32 v0, s8
	global_atomic_add v1, v0, s[4:5] offset:128
